# gather_u: the wave's 8 quantised token vectors kept in LDS (filled once), X planes read with ds_read_b128 per token-slice instead of global loads
# speedup vs baseline: 1.0055x; 1.0055x over previous
; __device__ void phase_gather_u(const Params& p) {
;     ...
; #pragma unroll 1
;   for (int r = 0; r < 4; ++r) {
; #pragma unroll 1
;     for (int t = tbase; t < T_TOK; t += tstride) {
;       const u32x4 ph = xq[((size_t)t * 64 + lane) * 2], pl = xq[((size_t)t * 64 + lane) * 2 + 1];
;       const int idA = idxg[(size_t)t * 128 + lane], idB = idxg[(size_t)t * 128 + 64 + lane];
;       unsigned long long m0 = __ballot((idA >> 12) == r), m1 = __ballot((idB >> 12) == r);
;       while (m0 | m1) {
;         int jk[16];
;         u32x4 rw[16];
;         const int nvalid = min((int)(__popcll(m0) + __popcll(m1)), 16);
;         int jfirst, efirst;
;         if (m0) { jfirst = __builtin_amdgcn_readfirstlane(__ffsll((long long)m0) - 1); efirst = __builtin_amdgcn_readlane(idA, jfirst); }
;         else { const int j1 = __builtin_amdgcn_readfirstlane(__ffsll((long long)m1) - 1); efirst = __builtin_amdgcn_readlane(idB, j1); jfirst = 64 + j1; }
; #pragma unroll
;         for (int k = 0; k < 16; ++k) {
;           int j = jfirst, e = efirst;
;           if (m0) { const int jj = __builtin_amdgcn_readfirstlane(__ffsll((long long)m0) - 1); m0 &= m0 - 1ull; j = jj; e = __builtin_amdgcn_readlane(idA, jj); }
;           else if (m1) { const int jj = __builtin_amdgcn_readfirstlane(__ffsll((long long)m1) - 1); m1 &= m1 - 1ull; j = 64 + jj; e = __builtin_amdgcn_readlane(idB, jj); }
;           jk[k] = j;
;           rw[k] = *(const u32x4*)(ub + (size_t)e * 1024 + lane * 16);
.LBB0_1205:
	s_or_b64 exec, exec, s[4:5]
	v_and_b32_e32 v0, 32, v139
	v_cmp_eq_u32_e64 s[2:3], 0, v0
	v_and_b32_e32 v0, 16, v139
	v_cmp_eq_u32_e64 s[4:5], 0, v0
	v_and_b32_e32 v0, 8, v139
	s_add_u32 s10, s34, 0xc000000
	v_cmp_eq_u32_e64 s[6:7], 0, v0
	v_mov_b32_e32 v1, 0
	v_lshlrev_b32_e32 v0, 5, v138
	s_addc_u32 s11, s35, 0
	s_waitcnt lgkmcnt(0)
	v_lshl_add_u64 v[2:3], s[34:35], 0, v[0:1]
	v_lshlrev_b32_e32 v0, 2, v138
	v_lshlrev_b32_e32 v82, 3, v139
	v_writelane_b32 v250, s10, 18
	v_mbcnt_hi_u32_b32 v83, -1, v30
	v_and_b32_e32 v4, 56, v82
	v_lshl_add_u64 v[76:77], s[10:11], 0, v[0:1]
	v_lshlrev_b32_e32 v0, 4, v138
	s_waitcnt vmcnt(0)
	v_lshl_add_u64 v[72:73], s[34:35], 0, v[0:1]
	v_and_b32_e32 v0, 64, v83
	s_add_u32 s70, s34, 0x17400000
	s_mov_b64 s[8:9], 0x15400000
	v_add_u32_e32 v84, 64, v0
	v_or_b32_e32 v0, v0, v4
	s_addc_u32 s71, s35, 0
	s_mov_b32 s33, 0
	v_lshl_add_u64 v[74:75], v[2:3], 0, s[8:9]
	v_writelane_b32 v250, s11, 19
	v_cmp_gt_u32_e64 s[8:9], 8, v138
	v_cmp_eq_u32_e64 s[10:11], 1, v138
	v_cmp_eq_u32_e64 s[12:13], 2, v138
	v_cmp_eq_u32_e64 s[14:15], 3, v138
	v_cmp_eq_u32_e64 s[16:17], 4, v138
	v_cmp_eq_u32_e64 s[18:19], 5, v138
	v_cmp_eq_u32_e64 s[20:21], 6, v138
	v_cmp_eq_u32_e64 s[22:23], 7, v138
	s_movk_i32 s48, 0x3fff
	v_xor_b32_e32 v89, 32, v83
	v_xor_b32_e32 v90, 16, v83
	v_xor_b32_e32 v88, 8, v83
	v_xor_b32_e32 v87, 4, v83
	v_xor_b32_e32 v86, 2, v83
	v_xor_b32_e32 v85, 1, v83
	v_lshlrev_b32_e32 v91, 2, v0
	v_and_b32_e32 v96, 15, v138
	v_lshrrev_b32_e32 v99, 4, v138
	v_lshlrev_b32_e32 v98, 2, v138
	v_lshrrev_b32_e32 v100, 6, v139
	v_cmp_eq_u32_e64 s[8:9], 0, v96
	v_lshlrev_b32_e32 v97, 5, v96
	v_lshlrev_b32_e32 v96, 4, v96
	v_readfirstlane_b32 s60, v100
	v_readfirstlane_b32 s61, v112
	s_add_u32 s64, s34, 0x15400000
	s_addc_u32 s65, s35, 0
	s_add_u32 s62, s34, 0xc000000
	s_addc_u32 s63, s35, 0
	s_lshl_b32 s60, s60, 10
	s_and_saveexec_b64 s[38:39], s[0:1]
	s_cbranch_execz .Lgu_done
	s_mov_b32 s33, 0
	s_mov_b32 s66, 0
	s_lshl_b32 s72, s60, 4
	s_add_i32 s72, s72, 0x2000
	v_lshlrev_b32_e32 v160, 5, v138
	v_add_u32_e32 v161, s72, v160
	s_mov_b32 s37, s61
	s_lshl_b32 s46, s37, 11
	s_add_u32 s46, s64, s46
	s_addc_u32 s47, s65, 0
	global_load_dwordx4 v[168:171], v160, s[46:47]
	global_load_dwordx4 v[172:175], v160, s[46:47] offset:16
	s_add_i32 s37, s61, 0x800
	s_lshl_b32 s46, s37, 11
	s_add_u32 s46, s64, s46
	s_addc_u32 s47, s65, 0
	global_load_dwordx4 v[176:179], v160, s[46:47]
	global_load_dwordx4 v[180:183], v160, s[46:47] offset:16
	s_add_i32 s37, s61, 0x1000
	s_lshl_b32 s46, s37, 11
	s_add_u32 s46, s64, s46
	s_addc_u32 s47, s65, 0
	global_load_dwordx4 v[184:187], v160, s[46:47]
	global_load_dwordx4 v[188:191], v160, s[46:47] offset:16
	s_add_i32 s37, s61, 0x1800
	s_lshl_b32 s46, s37, 11
	s_add_u32 s46, s64, s46
	s_addc_u32 s47, s65, 0
	global_load_dwordx4 v[192:195], v160, s[46:47]
	global_load_dwordx4 v[196:199], v160, s[46:47] offset:16
	s_add_i32 s37, s61, 0x2000
	s_lshl_b32 s46, s37, 11
	s_add_u32 s46, s64, s46
	s_addc_u32 s47, s65, 0
	global_load_dwordx4 v[200:203], v160, s[46:47]
	global_load_dwordx4 v[204:207], v160, s[46:47] offset:16
	s_add_i32 s37, s61, 0x2800
	s_lshl_b32 s46, s37, 11
	s_add_u32 s46, s64, s46
	s_addc_u32 s47, s65, 0
	global_load_dwordx4 v[208:211], v160, s[46:47]
	global_load_dwordx4 v[212:215], v160, s[46:47] offset:16
	s_add_i32 s37, s61, 0x3000
	s_lshl_b32 s46, s37, 11
	s_add_u32 s46, s64, s46
	s_addc_u32 s47, s65, 0
	global_load_dwordx4 v[216:219], v160, s[46:47]
	global_load_dwordx4 v[220:223], v160, s[46:47] offset:16
	s_add_i32 s37, s61, 0x3800
	s_lshl_b32 s46, s37, 11
	s_add_u32 s46, s64, s46
	s_addc_u32 s47, s65, 0
	global_load_dwordx4 v[224:227], v160, s[46:47]
	global_load_dwordx4 v[228:231], v160, s[46:47] offset:16
	s_waitcnt vmcnt(0)
	ds_write_b128 v161, v[168:171] offset:0
	ds_write_b128 v161, v[172:175] offset:16
	ds_write_b128 v161, v[176:179] offset:2048
	ds_write_b128 v161, v[180:183] offset:2064
	ds_write_b128 v161, v[184:187] offset:4096
	ds_write_b128 v161, v[188:191] offset:4112
	ds_write_b128 v161, v[192:195] offset:6144
	ds_write_b128 v161, v[196:199] offset:6160
	ds_write_b128 v161, v[200:203] offset:8192
	ds_write_b128 v161, v[204:207] offset:8208
	ds_write_b128 v161, v[208:211] offset:10240
	ds_write_b128 v161, v[212:215] offset:10256
	ds_write_b128 v161, v[216:219] offset:12288
	ds_write_b128 v161, v[220:223] offset:12304
	ds_write_b128 v161, v[224:227] offset:14336
	ds_write_b128 v161, v[228:231] offset:14352
	s_lshl_b32 s40, s61, 9
	s_add_u32 s40, s62, s40
	s_addc_u32 s41, s63, 0
	global_load_dword v94, v98, s[40:41]
	global_load_dword v95, v98, s[40:41] offset:256
	s_add_i32 s37, s61, s68
	s_lshl_b32 s40, s37, 9
	s_add_u32 s40, s62, s40
	s_addc_u32 s41, s63, 0
	global_load_dword v232, v98, s[40:41]
	global_load_dword v233, v98, s[40:41] offset:256
	s_waitcnt vmcnt(2)
	s_mov_b32 s67, 0xfffffc00

; __device__ void phase_gather_u(const Params& p) {
;     ...
;     for (int t = tbase; t < T_TOK; t += tstride) {
;       const u32x4 ph = xq[((size_t)t * 64 + lane) * 2], pl = xq[((size_t)t * 64 + lane) * 2 + 1];
;       const int idA = idxg[(size_t)t * 128 + lane], idB = idxg[(size_t)t * 128 + 64 + lane];
;       unsigned long long m0 = __ballot((idA >> 12) == r), m1 = __ballot((idB >> 12) == r);
.Lgu_tloop:
	s_lshl_b32 s37, s36, 9
	s_add_u32 s48, s70, s37
	s_addc_u32 s49, s71, 0
	s_waitcnt vmcnt(2)
	s_sub_i32 s37, s36, s61
	s_add_i32 s37, s37, s72
	v_add_u32_e32 v160, s37, v97
	ds_read_b128 v[0:3], v160
	ds_read_b128 v[4:7], v160 offset:16
	ds_read_b128 v[8:11], v160 offset:512
	ds_read_b128 v[12:15], v160 offset:528
	ds_read_b128 v[16:19], v160 offset:1024
	ds_read_b128 v[20:23], v160 offset:1040
	ds_read_b128 v[24:27], v160 offset:1536
	ds_read_b128 v[28:31], v160 offset:1552
	s_cmp_eq_u32 s66, 0
	s_cbranch_scc0 .Lgu_cpB
	v_mov_b32_e32 v92, v94
	v_mov_b32_e32 v93, v95
	s_branch .Lgu_cpdone
.Lgu_cpB:
	v_mov_b32_e32 v92, v232
	v_mov_b32_e32 v93, v233

; __device__ void phase_gather_u(const Params& p) {
;     ...
;     for (int t = tbase; t < T_TOK; t += tstride) {
;       const u32x4 ph = xq[((size_t)t * 64 + lane) * 2], pl = xq[((size_t)t * 64 + lane) * 2 + 1];
;       const int idA = idxg[(size_t)t * 128 + lane], idB = idxg[(size_t)t * 128 + 64 + lane];
.Lgu_tnext:
	s_lshl_b32 s37, s68, 1
	s_add_i32 s37, s37, s36
	s_sub_i32 s40, s37, 0x4000
	s_cmp_gt_i32 s37, 0x3fff
	s_cselect_b32 s37, s40, s37
	s_cmp_eq_u32 s66, 0
	s_cbranch_scc0 .Lgu_pfB
	s_lshl_b32 s40, s37, 9
	s_add_u32 s40, s62, s40
	s_addc_u32 s41, s63, 0
	global_load_dword v94, v98, s[40:41]
	global_load_dword v95, v98, s[40:41] offset:256
	s_branch .Lgu_pfdone
.Lgu_pfB:
	s_lshl_b32 s40, s37, 9
	s_add_u32 s40, s62, s40
	s_addc_u32 s41, s63, 0
	global_load_dword v232, v98, s[40:41]
	global_load_dword v233, v98, s[40:41] offset:256
